# prompt attention: both the unmasked and the causal-diagonal key-tile bodies hand-scheduled (mask = one compare + one select per element against a per-lane relative position)
# speedup vs baseline: 1.0042x; 1.0004x over previous
; #define LAS __attribute__((address_space(3)))
; #define MFMA32(a, b, c) __builtin_amdgcn_mfma_f32_32x32x16_bf16((a), (b), (c), 0, 0, 0)
; DI int crow(int r, int hi) { return (r & 3) + 8 * (r >> 2) + 4 * hi; }
; DI void attn_prompt_unit(const Args& a, LAS unsigned char* lds, int b, int h, int qb, float cB, int tid, int lane, int wave) {
;     ...
;         if (t * 64 <= qmax_w) {
;             const LAS bf16* Kb = Ks + buf * 6656; const LAS bf16* Vb = Vs + buf * 6144;
;             f32x16 p0, p1;
; #pragma unroll
;             for (int r = 0; r < 16; ++r) { p0[r] = -cB; p1[r] = -cB; }
; #pragma unroll
;             for (int s = 0; s < 6; ++s) { const bf16x8 k0 = *(const LAS bf16x8*)(Kb + r32 * 104 + 16 * s + 8 * h2), k1f = *(const LAS bf16x8*)(Kb + (32 + r32) * 104 + 16 * s + 8 * h2);
;                 p0 = MFMA32(k0, qf[s], p0); p1 = MFMA32(k1f, qf[s], p1); }
;             const bool diag = (t * 64 + 63 > qb * 256 + wave * 32);
; #pragma unroll
;             for (int r = 0; r < 16; ++r) { const int kv = t * 64 + crow(r, h2);
;                 float e0 = __builtin_amdgcn_exp2f(p0[r]), e1 = __builtin_amdgcn_exp2f(p1[r]);
;                 if (diag) { if (kv > qloc) e0 = 0.f; if (kv + 32 > qloc) e1 = 0.f; }
;                 p0[r] = e0; p1[r] = e1; lsum += e0 + e1; }
; #pragma unroll
;             for (int s4 = 0; s4 < 4; ++s4) { const bf16x8 pf = (s4 < 2) ? pack8(p0, s4 & 1) : pack8(p1, s4 & 1);
;                 o0 = MFMA32(tr_frag(Vb, 96, 16 * s4 + 4 * h2, 16 * s4 + 8 + 4 * h2, 0, lane), pf, o0); o1 = MFMA32(tr_frag(Vb, 96, 16 * s4 + 4 * h2, 16 * s4 + 8 + 4 * h2, 32, lane), pf, o1); }
.LBB0_841:
	s_or_b64 exec, exec, s[4:5]
	global_load_dwordx4 v[114:117], v[184:185], off
	s_and_b32 s36, s35, 1
	s_cmp_gt_i32 s34, s31
	s_cbranch_scc1 .LBB0_843
	s_add_i32 s4, s34, 63
	s_cmp_gt_i32 s4, s29
	s_cselect_b64 s[20:21], -1, 0
	s_cbranch_scc0 .Lpa_fast_0
	s_mul_i32 s4, s36, 0x3400
	v_add3_u32 v119, s4, v227, v126
	v_add3_u32 v121, s4, v228, v126
	s_mul_i32 s37, s36, 0x3000
	v_add_u32_e32 v133, s34, v118
	v_sub_u32_e32 v133, v178, v133
	ds_read_b128 v[50:53], v119
	ds_read_b128 v[54:57], v119 offset:32
	ds_read_b128 v[58:61], v119 offset:64
	ds_read_b128 v[62:65], v119 offset:96
	ds_read_b128 v[186:189], v119 offset:128
	ds_read_b128 v[190:193], v119 offset:160
	ds_read_b128 v[194:197], v121
	s_waitcnt lgkmcnt(6)
	v_mfma_f32_32x32x16_bf16 v[66:81], v[50:53], v[86:89], v[2:17]
	s_waitcnt lgkmcnt(5)
	v_mfma_f32_32x32x16_bf16 v[66:81], v[54:57], v[90:93], v[66:81]
	s_waitcnt lgkmcnt(4)
	v_mfma_f32_32x32x16_bf16 v[66:81], v[58:61], v[94:97], v[66:81]
	s_waitcnt lgkmcnt(3)
	v_mfma_f32_32x32x16_bf16 v[66:81], v[62:65], v[98:101], v[66:81]
	s_waitcnt lgkmcnt(2)
	v_mfma_f32_32x32x16_bf16 v[66:81], v[186:189], v[106:109], v[66:81]
	ds_read_b128 v[186:189], v121 offset:32
	s_waitcnt lgkmcnt(2)
	v_mfma_f32_32x32x16_bf16 v[66:81], v[190:193], v[102:105], v[66:81]
	ds_read_b128 v[190:193], v121 offset:64
	v_add_u32_e32 v119, s37, v229
	s_waitcnt lgkmcnt(2)
	v_mfma_f32_32x32x16_bf16 v[50:65], v[194:197], v[86:89], v[2:17]
	ds_read_b128 v[194:197], v121 offset:96
	s_waitcnt lgkmcnt(2)
	v_mfma_f32_32x32x16_bf16 v[50:65], v[186:189], v[90:93], v[50:65]
	ds_read_b128 v[186:189], v121 offset:128
	s_waitcnt lgkmcnt(2)
	v_mfma_f32_32x32x16_bf16 v[50:65], v[190:193], v[94:97], v[50:65]
	ds_read_b128 v[190:193], v121 offset:160
	s_waitcnt lgkmcnt(2)
	v_mfma_f32_32x32x16_bf16 v[50:65], v[194:197], v[98:101], v[50:65]
	v_exp_f32_e32 v66, v66
	v_exp_f32_e32 v67, v67
	v_exp_f32_e32 v68, v68
	v_exp_f32_e32 v69, v69
	s_waitcnt lgkmcnt(1)
	v_mfma_f32_32x32x16_bf16 v[50:65], v[186:189], v[106:109], v[50:65]
	v_exp_f32_e32 v70, v70
	v_exp_f32_e32 v71, v71
	v_exp_f32_e32 v72, v72
	v_exp_f32_e32 v73, v73
	s_waitcnt lgkmcnt(0)
	v_mfma_f32_32x32x16_bf16 v[50:65], v[190:193], v[102:105], v[50:65]
	v_exp_f32_e32 v74, v74
	v_exp_f32_e32 v75, v75
	v_exp_f32_e32 v76, v76
	v_exp_f32_e32 v77, v77
	v_exp_f32_e32 v78, v78
	v_exp_f32_e32 v79, v79
	v_exp_f32_e32 v80, v80
	v_exp_f32_e32 v81, v81
	ds_read_b64_tr_b16 v[186:187], v119 offset:26624
	ds_read_b64_tr_b16 v[188:189], v119 offset:28160
	ds_read_b64_tr_b16 v[194:195], v119 offset:26688
	ds_read_b64_tr_b16 v[196:197], v119 offset:28224
	v_cmp_gt_i32_e64 vcc, 0, v133
	v_cmp_gt_i32_e64 s[4:5], 1, v133
	v_cmp_gt_i32_e64 s[38:39], 2, v133
	v_cmp_gt_i32_e64 s[20:21], 3, v133
	v_cndmask_b32_e64 v66, v66, 0, vcc
	v_cndmask_b32_e64 v67, v67, 0, s[4:5]
	v_cndmask_b32_e64 v68, v68, 0, s[38:39]
	v_cndmask_b32_e64 v69, v69, 0, s[20:21]
	v_cmp_gt_i32_e64 vcc, 8, v133
	v_cmp_gt_i32_e64 s[4:5], 9, v133
	v_cmp_gt_i32_e64 s[38:39], 10, v133
	v_cmp_gt_i32_e64 s[20:21], 11, v133
	v_cndmask_b32_e64 v70, v70, 0, vcc
	v_cndmask_b32_e64 v71, v71, 0, s[4:5]
	v_cndmask_b32_e64 v72, v72, 0, s[38:39]
	v_cndmask_b32_e64 v73, v73, 0, s[20:21]
	v_add_f32_e32 v1, v1, v66
	v_add_f32_e32 v1, v1, v67
	v_add_f32_e32 v1, v1, v68
	v_add_f32_e32 v1, v1, v69
	v_add_f32_e32 v1, v1, v70
	v_add_f32_e32 v1, v1, v71
	v_add_f32_e32 v1, v1, v72
	v_add_f32_e32 v1, v1, v73
	v_cvt_pk_bf16_f32 v66, v66, v67
	v_cvt_pk_bf16_f32 v67, v68, v69
	v_cvt_pk_bf16_f32 v68, v70, v71
	v_cvt_pk_bf16_f32 v69, v72, v73
	s_nop 0
	s_waitcnt lgkmcnt(0)
; #define MFMA32(a, b, c) __builtin_amdgcn_mfma_f32_32x32x16_bf16((a), (b), (c), 0, 0, 0)
; DI int crow(int r, int hi) { return (r & 3) + 8 * (r >> 2) + 4 * hi; }
; DI void attn_prompt_unit(const Args& a, LAS unsigned char* lds, int b, int h, int qb, float cB, int tid, int lane, int wave) {
;     ...
; #pragma unroll
;             for (int r = 0; r < 16; ++r) { const int kv = t * 64 + crow(r, h2);
;                 float e0 = __builtin_amdgcn_exp2f(p0[r]), e1 = __builtin_amdgcn_exp2f(p1[r]);
;                 if (diag) { if (kv > qloc) e0 = 0.f; if (kv + 32 > qloc) e1 = 0.f; }
;                 p0[r] = e0; p1[r] = e1; lsum += e0 + e1; }
; #pragma unroll
;             for (int s4 = 0; s4 < 4; ++s4) { const bf16x8 pf = (s4 < 2) ? pack8(p0, s4 & 1) : pack8(p1, s4 & 1);
;                 o0 = MFMA32(tr_frag(Vb, 96, 16 * s4 + 4 * h2, 16 * s4 + 8 + 4 * h2, 0, lane), pf, o0); o1 = MFMA32(tr_frag(Vb, 96, 16 * s4 + 4 * h2, 16 * s4 + 8 + 4 * h2, 32, lane), pf, o1); }
	v_mfma_f32_32x32x16_bf16 v[18:33], v[186:189], v[66:69], v[18:33]
	ds_read_b64_tr_b16 v[190:191], v119 offset:29696
	ds_read_b64_tr_b16 v[192:193], v119 offset:31232
	v_mfma_f32_32x32x16_bf16 v[34:49], v[194:197], v[66:69], v[34:49]
	ds_read_b64_tr_b16 v[186:187], v119 offset:29760
	ds_read_b64_tr_b16 v[188:189], v119 offset:31296
	v_exp_f32_e32 v50, v50
	v_exp_f32_e32 v51, v51
	v_exp_f32_e32 v52, v52
	v_exp_f32_e32 v53, v53
	v_exp_f32_e32 v54, v54
	v_exp_f32_e32 v55, v55
	v_exp_f32_e32 v56, v56
	v_exp_f32_e32 v57, v57
	v_cmp_gt_i32_e64 vcc, 16, v133
	v_cmp_gt_i32_e64 s[4:5], 17, v133
	v_cmp_gt_i32_e64 s[38:39], 18, v133
	v_cmp_gt_i32_e64 s[20:21], 19, v133
	v_cndmask_b32_e64 v74, v74, 0, vcc
	v_cndmask_b32_e64 v75, v75, 0, s[4:5]
	v_cndmask_b32_e64 v76, v76, 0, s[38:39]
	v_cndmask_b32_e64 v77, v77, 0, s[20:21]
	v_cmp_gt_i32_e64 vcc, 24, v133
	v_cmp_gt_i32_e64 s[4:5], 25, v133
	v_cmp_gt_i32_e64 s[38:39], 26, v133
	v_cmp_gt_i32_e64 s[20:21], 27, v133
	v_cndmask_b32_e64 v78, v78, 0, vcc
	v_cndmask_b32_e64 v79, v79, 0, s[4:5]
	v_cndmask_b32_e64 v80, v80, 0, s[38:39]
	v_cndmask_b32_e64 v81, v81, 0, s[20:21]
	v_add_f32_e32 v1, v1, v74
	v_add_f32_e32 v1, v1, v75
	v_add_f32_e32 v1, v1, v76
	v_add_f32_e32 v1, v1, v77
	v_add_f32_e32 v1, v1, v78
	v_add_f32_e32 v1, v1, v79
	v_add_f32_e32 v1, v1, v80
	v_add_f32_e32 v1, v1, v81
	v_cvt_pk_bf16_f32 v74, v74, v75
	v_cvt_pk_bf16_f32 v75, v76, v77
	v_cvt_pk_bf16_f32 v76, v78, v79
	v_cvt_pk_bf16_f32 v77, v80, v81
	s_nop 0
	s_waitcnt lgkmcnt(0)
	v_mfma_f32_32x32x16_bf16 v[18:33], v[190:193], v[74:77], v[18:33]
	ds_read_b64_tr_b16 v[194:195], v119 offset:32768
	ds_read_b64_tr_b16 v[196:197], v119 offset:34304
	v_mfma_f32_32x32x16_bf16 v[34:49], v[186:189], v[74:77], v[34:49]
	ds_read_b64_tr_b16 v[190:191], v119 offset:32832
	ds_read_b64_tr_b16 v[192:193], v119 offset:34368
	v_exp_f32_e32 v58, v58
	v_exp_f32_e32 v59, v59
	v_exp_f32_e32 v60, v60
	v_exp_f32_e32 v61, v61
	v_exp_f32_e32 v62, v62
	v_exp_f32_e32 v63, v63
	v_exp_f32_e32 v64, v64
	v_exp_f32_e32 v65, v65
	v_cmp_gt_i32_e64 vcc, 32, v133
	v_cmp_gt_i32_e64 s[4:5], 33, v133
	v_cmp_gt_i32_e64 s[38:39], 34, v133
	v_cmp_gt_i32_e64 s[20:21], 35, v133
	v_cndmask_b32_e64 v50, v50, 0, vcc
	v_cndmask_b32_e64 v51, v51, 0, s[4:5]
	v_cndmask_b32_e64 v52, v52, 0, s[38:39]
	v_cndmask_b32_e64 v53, v53, 0, s[20:21]
	v_cmp_gt_i32_e64 vcc, 40, v133
	v_cmp_gt_i32_e64 s[4:5], 41, v133
	v_cmp_gt_i32_e64 s[38:39], 42, v133
	v_cmp_gt_i32_e64 s[20:21], 43, v133
	v_cndmask_b32_e64 v54, v54, 0, vcc
	v_cndmask_b32_e64 v55, v55, 0, s[4:5]
	v_cndmask_b32_e64 v56, v56, 0, s[38:39]
	v_cndmask_b32_e64 v57, v57, 0, s[20:21]
	v_add_f32_e32 v121, v50, v51
	v_add_f32_e32 v121, v121, v52
	v_add_f32_e32 v121, v121, v53
	v_add_f32_e32 v121, v121, v54
	v_add_f32_e32 v121, v121, v55
	v_add_f32_e32 v121, v121, v56
	v_add_f32_e32 v121, v121, v57
	v_cvt_pk_bf16_f32 v50, v50, v51
	v_cvt_pk_bf16_f32 v51, v52, v53
	v_cvt_pk_bf16_f32 v52, v54, v55
	v_cvt_pk_bf16_f32 v53, v56, v57
	s_nop 0
	s_waitcnt lgkmcnt(0)
	v_mfma_f32_32x32x16_bf16 v[18:33], v[194:197], v[50:53], v[18:33]
	ds_read_b64_tr_b16 v[186:187], v119 offset:35840
	ds_read_b64_tr_b16 v[188:189], v119 offset:37376
	v_mfma_f32_32x32x16_bf16 v[34:49], v[190:193], v[50:53], v[34:49]
	ds_read_b64_tr_b16 v[194:195], v119 offset:35904
	ds_read_b64_tr_b16 v[196:197], v119 offset:37440
	v_cmp_gt_i32_e64 vcc, 48, v133
	v_cmp_gt_i32_e64 s[4:5], 49, v133
	v_cmp_gt_i32_e64 s[38:39], 50, v133
	v_cmp_gt_i32_e64 s[20:21], 51, v133
	v_cndmask_b32_e64 v58, v58, 0, vcc
	v_cndmask_b32_e64 v59, v59, 0, s[4:5]
	v_cndmask_b32_e64 v60, v60, 0, s[38:39]
	v_cndmask_b32_e64 v61, v61, 0, s[20:21]
	v_cmp_gt_i32_e64 vcc, 56, v133
	v_cmp_gt_i32_e64 s[4:5], 57, v133
	v_cmp_gt_i32_e64 s[38:39], 58, v133
	v_cmp_gt_i32_e64 s[20:21], 59, v133
	v_cndmask_b32_e64 v62, v62, 0, vcc
	v_cndmask_b32_e64 v63, v63, 0, s[4:5]
	v_cndmask_b32_e64 v64, v64, 0, s[38:39]
	v_cndmask_b32_e64 v65, v65, 0, s[20:21]
	v_add_f32_e32 v121, v121, v58
	v_add_f32_e32 v121, v121, v59
	v_add_f32_e32 v121, v121, v60
	v_add_f32_e32 v121, v121, v61
	v_add_f32_e32 v121, v121, v62
	v_add_f32_e32 v121, v121, v63
	v_add_f32_e32 v121, v121, v64
	v_add_f32_e32 v121, v121, v65
	v_cvt_pk_bf16_f32 v58, v58, v59
	v_cvt_pk_bf16_f32 v59, v60, v61
	v_cvt_pk_bf16_f32 v60, v62, v63
	v_cvt_pk_bf16_f32 v61, v64, v65
	s_nop 0
	s_waitcnt lgkmcnt(0)
	v_mfma_f32_32x32x16_bf16 v[18:33], v[186:189], v[58:61], v[18:33]
	v_add_f32_e32 v1, v1, v121
	v_mfma_f32_32x32x16_bf16 v[34:49], v[194:197], v[58:61], v[34:49]
	s_branch .LBB0_843

; #define LAS __attribute__((address_space(3)))
; #define MFMA32(a, b, c) __builtin_amdgcn_mfma_f32_32x32x16_bf16((a), (b), (c), 0, 0, 0)
; DI int crow(int r, int hi) { return (r & 3) + 8 * (r >> 2) + 4 * hi; }
; DI void attn_prompt_unit(const Args& a, LAS unsigned char* lds, int b, int h, int qb, float cB, int tid, int lane, int wave) {
;     ...
;         if (t * 64 <= qmax_w) {
;             const LAS bf16* Kb = Ks + buf * 6656; const LAS bf16* Vb = Vs + buf * 6144;
;             f32x16 p0, p1;
; #pragma unroll
;             for (int r = 0; r < 16; ++r) { p0[r] = -cB; p1[r] = -cB; }
; #pragma unroll
;             for (int s = 0; s < 6; ++s) { const bf16x8 k0 = *(const LAS bf16x8*)(Kb + r32 * 104 + 16 * s + 8 * h2), k1f = *(const LAS bf16x8*)(Kb + (32 + r32) * 104 + 16 * s + 8 * h2);
;                 p0 = MFMA32(k0, qf[s], p0); p1 = MFMA32(k1f, qf[s], p1); }
;             const bool diag = (t * 64 + 63 > qb * 256 + wave * 32);
; #pragma unroll
;             for (int r = 0; r < 16; ++r) { const int kv = t * 64 + crow(r, h2);
;                 float e0 = __builtin_amdgcn_exp2f(p0[r]), e1 = __builtin_amdgcn_exp2f(p1[r]);
;                 if (diag) { if (kv > qloc) e0 = 0.f; if (kv + 32 > qloc) e1 = 0.f; }
;                 p0[r] = e0; p1[r] = e1; lsum += e0 + e1; }
; #pragma unroll
;             for (int s4 = 0; s4 < 4; ++s4) { const bf16x8 pf = (s4 < 2) ? pack8(p0, s4 & 1) : pack8(p1, s4 & 1);
;                 o0 = MFMA32(tr_frag(Vb, 96, 16 * s4 + 4 * h2, 16 * s4 + 8 + 4 * h2, 0, lane), pf, o0); o1 = MFMA32(tr_frag(Vb, 96, 16 * s4 + 4 * h2, 16 * s4 + 8 + 4 * h2, 32, lane), pf, o1); }
.LBB0_855:
	s_or_b64 exec, exec, s[4:5]
	global_load_dwordx4 v[114:117], v[162:163], off
	s_and_b32 s28, s27, 1
	s_cmp_gt_i32 s21, s19
	s_cbranch_scc1 .LBB0_857
	s_add_i32 s4, s21, 63
	s_cmp_gt_i32 s4, s20
	s_cselect_b64 s[16:17], -1, 0
	s_cbranch_scc0 .Lpa_fast_1
	s_mul_i32 s4, s28, 0x3400
	v_add3_u32 v119, s4, v227, v126
	v_add3_u32 v121, s4, v228, v126
	s_mul_i32 s29, s28, 0x3000
	v_add_u32_e32 v133, s21, v118
	v_sub_u32_e32 v133, v178, v133
	ds_read_b128 v[50:53], v119
	ds_read_b128 v[54:57], v119 offset:32
	ds_read_b128 v[58:61], v119 offset:64
	ds_read_b128 v[62:65], v119 offset:96
	ds_read_b128 v[168:171], v119 offset:128
	ds_read_b128 v[172:175], v119 offset:160
	ds_read_b128 v[180:183], v121
	s_waitcnt lgkmcnt(6)
	v_mfma_f32_32x32x16_bf16 v[66:81], v[50:53], v[86:89], v[2:17]
	s_waitcnt lgkmcnt(5)
	v_mfma_f32_32x32x16_bf16 v[66:81], v[54:57], v[90:93], v[66:81]
	s_waitcnt lgkmcnt(4)
	v_mfma_f32_32x32x16_bf16 v[66:81], v[58:61], v[94:97], v[66:81]
	s_waitcnt lgkmcnt(3)
	v_mfma_f32_32x32x16_bf16 v[66:81], v[62:65], v[98:101], v[66:81]
	s_waitcnt lgkmcnt(2)
	v_mfma_f32_32x32x16_bf16 v[66:81], v[168:171], v[106:109], v[66:81]
	ds_read_b128 v[168:171], v121 offset:32
	s_waitcnt lgkmcnt(2)
	v_mfma_f32_32x32x16_bf16 v[66:81], v[172:175], v[102:105], v[66:81]
	ds_read_b128 v[172:175], v121 offset:64
	v_add_u32_e32 v119, s29, v229
	s_waitcnt lgkmcnt(2)
	v_mfma_f32_32x32x16_bf16 v[50:65], v[180:183], v[86:89], v[2:17]
	ds_read_b128 v[180:183], v121 offset:96
	s_waitcnt lgkmcnt(2)
	v_mfma_f32_32x32x16_bf16 v[50:65], v[168:171], v[90:93], v[50:65]
	ds_read_b128 v[168:171], v121 offset:128
	s_waitcnt lgkmcnt(2)
	v_mfma_f32_32x32x16_bf16 v[50:65], v[172:175], v[94:97], v[50:65]
	ds_read_b128 v[172:175], v121 offset:160
	s_waitcnt lgkmcnt(2)
	v_mfma_f32_32x32x16_bf16 v[50:65], v[180:183], v[98:101], v[50:65]
	v_exp_f32_e32 v66, v66
	v_exp_f32_e32 v67, v67
	v_exp_f32_e32 v68, v68
	v_exp_f32_e32 v69, v69
	s_waitcnt lgkmcnt(1)
	v_mfma_f32_32x32x16_bf16 v[50:65], v[168:171], v[106:109], v[50:65]
	v_exp_f32_e32 v70, v70
	v_exp_f32_e32 v71, v71
	v_exp_f32_e32 v72, v72
	v_exp_f32_e32 v73, v73
	s_waitcnt lgkmcnt(0)
	v_mfma_f32_32x32x16_bf16 v[50:65], v[172:175], v[102:105], v[50:65]
	v_exp_f32_e32 v74, v74
	v_exp_f32_e32 v75, v75
	v_exp_f32_e32 v76, v76
	v_exp_f32_e32 v77, v77
	v_exp_f32_e32 v78, v78
	v_exp_f32_e32 v79, v79
	v_exp_f32_e32 v80, v80
	v_exp_f32_e32 v81, v81
	ds_read_b64_tr_b16 v[168:169], v119 offset:26624
	ds_read_b64_tr_b16 v[170:171], v119 offset:28160
	ds_read_b64_tr_b16 v[180:181], v119 offset:26688
	ds_read_b64_tr_b16 v[182:183], v119 offset:28224
	v_cmp_gt_i32_e64 vcc, 0, v133
	v_cmp_gt_i32_e64 s[4:5], 1, v133
	v_cmp_gt_i32_e64 s[30:31], 2, v133
	v_cmp_gt_i32_e64 s[16:17], 3, v133
	v_cndmask_b32_e64 v66, v66, 0, vcc
	v_cndmask_b32_e64 v67, v67, 0, s[4:5]
	v_cndmask_b32_e64 v68, v68, 0, s[30:31]
	v_cndmask_b32_e64 v69, v69, 0, s[16:17]
	v_cmp_gt_i32_e64 vcc, 8, v133
	v_cmp_gt_i32_e64 s[4:5], 9, v133
	v_cmp_gt_i32_e64 s[30:31], 10, v133
	v_cmp_gt_i32_e64 s[16:17], 11, v133
	v_cndmask_b32_e64 v70, v70, 0, vcc
	v_cndmask_b32_e64 v71, v71, 0, s[4:5]
	v_cndmask_b32_e64 v72, v72, 0, s[30:31]
	v_cndmask_b32_e64 v73, v73, 0, s[16:17]
	v_add_f32_e32 v1, v1, v66
	v_add_f32_e32 v1, v1, v67
	v_add_f32_e32 v1, v1, v68
	v_add_f32_e32 v1, v1, v69
	v_add_f32_e32 v1, v1, v70
	v_add_f32_e32 v1, v1, v71
	v_add_f32_e32 v1, v1, v72
	v_add_f32_e32 v1, v1, v73
	v_cvt_pk_bf16_f32 v66, v66, v67
	v_cvt_pk_bf16_f32 v67, v68, v69
	v_cvt_pk_bf16_f32 v68, v70, v71
	v_cvt_pk_bf16_f32 v69, v72, v73
	s_nop 0
	s_waitcnt lgkmcnt(0)
; #define MFMA32(a, b, c) __builtin_amdgcn_mfma_f32_32x32x16_bf16((a), (b), (c), 0, 0, 0)
; DI int crow(int r, int hi) { return (r & 3) + 8 * (r >> 2) + 4 * hi; }
; DI void attn_prompt_unit(const Args& a, LAS unsigned char* lds, int b, int h, int qb, float cB, int tid, int lane, int wave) {
;     ...
; #pragma unroll
;             for (int r = 0; r < 16; ++r) { const int kv = t * 64 + crow(r, h2);
;                 float e0 = __builtin_amdgcn_exp2f(p0[r]), e1 = __builtin_amdgcn_exp2f(p1[r]);
;                 if (diag) { if (kv > qloc) e0 = 0.f; if (kv + 32 > qloc) e1 = 0.f; }
;                 p0[r] = e0; p1[r] = e1; lsum += e0 + e1; }
; #pragma unroll
;             for (int s4 = 0; s4 < 4; ++s4) { const bf16x8 pf = (s4 < 2) ? pack8(p0, s4 & 1) : pack8(p1, s4 & 1);
;                 o0 = MFMA32(tr_frag(Vb, 96, 16 * s4 + 4 * h2, 16 * s4 + 8 + 4 * h2, 0, lane), pf, o0); o1 = MFMA32(tr_frag(Vb, 96, 16 * s4 + 4 * h2, 16 * s4 + 8 + 4 * h2, 32, lane), pf, o1); }
	v_mfma_f32_32x32x16_bf16 v[18:33], v[168:171], v[66:69], v[18:33]
	ds_read_b64_tr_b16 v[172:173], v119 offset:29696
	ds_read_b64_tr_b16 v[174:175], v119 offset:31232
	v_mfma_f32_32x32x16_bf16 v[34:49], v[180:183], v[66:69], v[34:49]
	ds_read_b64_tr_b16 v[168:169], v119 offset:29760
	ds_read_b64_tr_b16 v[170:171], v119 offset:31296
	v_exp_f32_e32 v50, v50
	v_exp_f32_e32 v51, v51
	v_exp_f32_e32 v52, v52
	v_exp_f32_e32 v53, v53
	v_exp_f32_e32 v54, v54
	v_exp_f32_e32 v55, v55
	v_exp_f32_e32 v56, v56
	v_exp_f32_e32 v57, v57
	v_cmp_gt_i32_e64 vcc, 16, v133
	v_cmp_gt_i32_e64 s[4:5], 17, v133
	v_cmp_gt_i32_e64 s[30:31], 18, v133
	v_cmp_gt_i32_e64 s[16:17], 19, v133
	v_cndmask_b32_e64 v74, v74, 0, vcc
	v_cndmask_b32_e64 v75, v75, 0, s[4:5]
	v_cndmask_b32_e64 v76, v76, 0, s[30:31]
	v_cndmask_b32_e64 v77, v77, 0, s[16:17]
	v_cmp_gt_i32_e64 vcc, 24, v133
	v_cmp_gt_i32_e64 s[4:5], 25, v133
	v_cmp_gt_i32_e64 s[30:31], 26, v133
	v_cmp_gt_i32_e64 s[16:17], 27, v133
	v_cndmask_b32_e64 v78, v78, 0, vcc
	v_cndmask_b32_e64 v79, v79, 0, s[4:5]
	v_cndmask_b32_e64 v80, v80, 0, s[30:31]
	v_cndmask_b32_e64 v81, v81, 0, s[16:17]
	v_add_f32_e32 v1, v1, v74
	v_add_f32_e32 v1, v1, v75
	v_add_f32_e32 v1, v1, v76
	v_add_f32_e32 v1, v1, v77
	v_add_f32_e32 v1, v1, v78
	v_add_f32_e32 v1, v1, v79
	v_add_f32_e32 v1, v1, v80
	v_add_f32_e32 v1, v1, v81
	v_cvt_pk_bf16_f32 v74, v74, v75
	v_cvt_pk_bf16_f32 v75, v76, v77
	v_cvt_pk_bf16_f32 v76, v78, v79
	v_cvt_pk_bf16_f32 v77, v80, v81
	s_nop 0
	s_waitcnt lgkmcnt(0)
	v_mfma_f32_32x32x16_bf16 v[18:33], v[172:175], v[74:77], v[18:33]
	ds_read_b64_tr_b16 v[180:181], v119 offset:32768
	ds_read_b64_tr_b16 v[182:183], v119 offset:34304
	v_mfma_f32_32x32x16_bf16 v[34:49], v[168:171], v[74:77], v[34:49]
	ds_read_b64_tr_b16 v[172:173], v119 offset:32832
	ds_read_b64_tr_b16 v[174:175], v119 offset:34368
	v_exp_f32_e32 v58, v58
	v_exp_f32_e32 v59, v59
	v_exp_f32_e32 v60, v60
	v_exp_f32_e32 v61, v61
	v_exp_f32_e32 v62, v62
	v_exp_f32_e32 v63, v63
	v_exp_f32_e32 v64, v64
	v_exp_f32_e32 v65, v65
	v_cmp_gt_i32_e64 vcc, 32, v133
	v_cmp_gt_i32_e64 s[4:5], 33, v133
	v_cmp_gt_i32_e64 s[30:31], 34, v133
	v_cmp_gt_i32_e64 s[16:17], 35, v133
	v_cndmask_b32_e64 v50, v50, 0, vcc
	v_cndmask_b32_e64 v51, v51, 0, s[4:5]
	v_cndmask_b32_e64 v52, v52, 0, s[30:31]
	v_cndmask_b32_e64 v53, v53, 0, s[16:17]
	v_cmp_gt_i32_e64 vcc, 40, v133
	v_cmp_gt_i32_e64 s[4:5], 41, v133
	v_cmp_gt_i32_e64 s[30:31], 42, v133
	v_cmp_gt_i32_e64 s[16:17], 43, v133
	v_cndmask_b32_e64 v54, v54, 0, vcc
	v_cndmask_b32_e64 v55, v55, 0, s[4:5]
	v_cndmask_b32_e64 v56, v56, 0, s[30:31]
	v_cndmask_b32_e64 v57, v57, 0, s[16:17]
	v_add_f32_e32 v121, v50, v51
	v_add_f32_e32 v121, v121, v52
	v_add_f32_e32 v121, v121, v53
	v_add_f32_e32 v121, v121, v54
	v_add_f32_e32 v121, v121, v55
	v_add_f32_e32 v121, v121, v56
	v_add_f32_e32 v121, v121, v57
	v_cvt_pk_bf16_f32 v50, v50, v51
	v_cvt_pk_bf16_f32 v51, v52, v53
	v_cvt_pk_bf16_f32 v52, v54, v55
	v_cvt_pk_bf16_f32 v53, v56, v57
	s_nop 0
	s_waitcnt lgkmcnt(0)
	v_mfma_f32_32x32x16_bf16 v[18:33], v[180:183], v[50:53], v[18:33]
	ds_read_b64_tr_b16 v[168:169], v119 offset:35840
	ds_read_b64_tr_b16 v[170:171], v119 offset:37376
	v_mfma_f32_32x32x16_bf16 v[34:49], v[172:175], v[50:53], v[34:49]
	ds_read_b64_tr_b16 v[180:181], v119 offset:35904
	ds_read_b64_tr_b16 v[182:183], v119 offset:37440
	v_cmp_gt_i32_e64 vcc, 48, v133
	v_cmp_gt_i32_e64 s[4:5], 49, v133
	v_cmp_gt_i32_e64 s[30:31], 50, v133
	v_cmp_gt_i32_e64 s[16:17], 51, v133
	v_cndmask_b32_e64 v58, v58, 0, vcc
	v_cndmask_b32_e64 v59, v59, 0, s[4:5]
	v_cndmask_b32_e64 v60, v60, 0, s[30:31]
	v_cndmask_b32_e64 v61, v61, 0, s[16:17]
	v_cmp_gt_i32_e64 vcc, 56, v133
	v_cmp_gt_i32_e64 s[4:5], 57, v133
	v_cmp_gt_i32_e64 s[30:31], 58, v133
	v_cmp_gt_i32_e64 s[16:17], 59, v133
	v_cndmask_b32_e64 v62, v62, 0, vcc
	v_cndmask_b32_e64 v63, v63, 0, s[4:5]
	v_cndmask_b32_e64 v64, v64, 0, s[30:31]
	v_cndmask_b32_e64 v65, v65, 0, s[16:17]
	v_add_f32_e32 v121, v121, v58
	v_add_f32_e32 v121, v121, v59
	v_add_f32_e32 v121, v121, v60
	v_add_f32_e32 v121, v121, v61
	v_add_f32_e32 v121, v121, v62
	v_add_f32_e32 v121, v121, v63
	v_add_f32_e32 v121, v121, v64
	v_add_f32_e32 v121, v121, v65
	v_cvt_pk_bf16_f32 v58, v58, v59
	v_cvt_pk_bf16_f32 v59, v60, v61
	v_cvt_pk_bf16_f32 v60, v62, v63
	v_cvt_pk_bf16_f32 v61, v64, v65
	s_nop 0
	s_waitcnt lgkmcnt(0)
	v_mfma_f32_32x32x16_bf16 v[18:33], v[168:171], v[58:61], v[18:33]
	v_add_f32_e32 v1, v1, v121
	v_mfma_f32_32x32x16_bf16 v[34:49], v[180:183], v[58:61], v[34:49]
	s_branch .LBB0_857
